# grid barrier polls spaced by s_sleep 8 instead of s_sleep 1 (less same-address polling pressure on the arrival atomics)
# speedup vs baseline: 1.0020x; 1.0020x over previous
.LBB0_62:
	s_sleep 8
	global_load_dword v1, v2, s[10:11] offset:32 sc1
	s_waitcnt vmcnt(0)
	v_and_b32_e32 v1, 0xffff0000, v1
	v_cmp_ne_u32_e32 vcc, v1, v3
	s_or_b64 s[12:13], vcc, s[12:13]
	s_andn2_b64 exec, exec, s[12:13]
	s_cbranch_execnz .LBB0_62

.LBB0_70:
	global_load_dword v17, v18, s[12:13] sc1
	global_load_dword v2, v18, s[14:15] sc1
	global_load_dword v3, v18, s[16:17] sc1
	global_load_dword v4, v18, s[18:19] sc1
	global_load_dword v5, v18, s[20:21] sc1
	global_load_dword v6, v18, s[22:23] sc1
	global_load_dword v7, v18, s[24:25] sc1
	global_load_dword v8, v18, s[26:27] sc1
	global_load_dword v9, v18, s[28:29] sc1
	global_load_dword v10, v18, s[30:31] sc1
	global_load_dword v11, v18, s[34:35] sc1
	global_load_dword v12, v18, s[36:37] sc1
	global_load_dword v13, v18, s[38:39] sc1
	global_load_dword v14, v18, s[40:41] sc1
	global_load_dword v15, v18, s[42:43] sc1
	global_load_dword v16, v18, s[44:45] sc1
	s_mov_b64 s[46:47], -1
	s_mov_b64 s[48:49], -1
	s_waitcnt vmcnt(14)
	v_add_u32_e32 v1, v2, v17
	s_waitcnt vmcnt(13)
	v_add_u32_e32 v1, v1, v3
	s_waitcnt vmcnt(12)
	v_add_u32_e32 v1, v1, v4
	s_waitcnt vmcnt(11)
	v_add_u32_e32 v1, v1, v5
	s_waitcnt vmcnt(10)
	v_add_u32_e32 v1, v1, v6
	s_waitcnt vmcnt(9)
	v_add_u32_e32 v1, v1, v7
	s_waitcnt vmcnt(8)
	v_add_u32_e32 v1, v1, v8
	s_waitcnt vmcnt(7)
	v_add_u32_e32 v1, v1, v9
	s_waitcnt vmcnt(6)
	v_add_u32_e32 v1, v1, v10
	s_waitcnt vmcnt(5)
	v_add_u32_e32 v1, v1, v11
	s_waitcnt vmcnt(4)
	v_add_u32_e32 v1, v1, v12
	s_waitcnt vmcnt(3)
	v_add_u32_e32 v1, v1, v13
	s_waitcnt vmcnt(2)
	v_add_u32_e32 v1, v1, v14
	s_waitcnt vmcnt(1)
	v_add_u32_e32 v1, v1, v15
	s_waitcnt vmcnt(0)
	v_add_u32_e32 v1, v1, v16
	v_cmp_eq_u32_e32 vcc, s3, v1
	s_cbranch_vccnz .LBB0_69
	s_and_b32 s7, s6, 0xff
	s_cmp_eq_u32 s7, 0
	s_mov_b64 s[50:51], -1
	s_sleep 8
	s_cbranch_scc0 .LBB0_74
	global_load_dword v1, v18, s[10:11] sc1
	s_waitcnt vmcnt(0)
	v_cmp_eq_u32_e32 vcc, 0, v1
	s_cbranch_vccnz .LBB0_76
	s_mov_b64 s[50:51], 0

.LBB0_88:
	s_and_b32 s6, s3, 0xff
	s_mov_b64 s[24:25], -1
	s_cmp_lg_u32 s6, 0
	s_mov_b64 s[28:29], -1
	s_sleep 8
	s_cbranch_scc1 .LBB0_91
	global_load_dword v1, v2, s[16:17] sc1
	s_waitcnt vmcnt(0)
	v_cmp_eq_u32_e32 vcc, 0, v1
	s_cbranch_vccnz .LBB0_93
	s_mov_b64 s[28:29], 0
	s_mov_b64 s[26:27], -1

.LBB0_105:
	s_and_b32 s6, s3, 0xff
	s_cmp_lg_u32 s6, 0
	s_mov_b64 s[26:27], -1
	s_sleep 8
	s_cbranch_scc1 .LBB0_108
	global_load_dword v1, v2, s[16:17] sc1
	s_waitcnt vmcnt(0)
	v_cmp_eq_u32_e32 vcc, 0, v1
	s_cbranch_vccnz .LBB0_110
	s_mov_b64 s[26:27], 0
	s_mov_b64 s[24:25], -1

.LBB0_144:
	s_sleep 8
	global_load_dword v1, v2, s[8:9] offset:32 sc1
	s_waitcnt vmcnt(0)
	v_and_b32_e32 v1, 0xffff0000, v1
	v_cmp_ne_u32_e32 vcc, v1, v3
	s_or_b64 s[10:11], vcc, s[10:11]
	s_andn2_b64 exec, exec, s[10:11]
	s_cbranch_execnz .LBB0_144

.LBB0_152:
	global_load_dword v17, v18, s[10:11] sc1
	global_load_dword v2, v18, s[12:13] sc1
	global_load_dword v3, v18, s[14:15] sc1
	global_load_dword v4, v18, s[16:17] sc1
	global_load_dword v5, v18, s[18:19] sc1
	global_load_dword v6, v18, s[20:21] sc1
	global_load_dword v7, v18, s[22:23] sc1
	global_load_dword v8, v18, s[24:25] sc1
	global_load_dword v9, v18, s[26:27] sc1
	global_load_dword v10, v18, s[28:29] sc1
	global_load_dword v11, v18, s[30:31] sc1
	global_load_dword v12, v18, s[34:35] sc1
	global_load_dword v13, v18, s[36:37] sc1
	global_load_dword v14, v18, s[38:39] sc1
	global_load_dword v15, v18, s[40:41] sc1
	global_load_dword v16, v18, s[42:43] sc1
	s_mov_b64 s[44:45], -1
	s_mov_b64 s[46:47], -1
	s_waitcnt vmcnt(14)
	v_add_u32_e32 v1, v2, v17
	s_waitcnt vmcnt(13)
	v_add_u32_e32 v1, v1, v3
	s_waitcnt vmcnt(12)
	v_add_u32_e32 v1, v1, v4
	s_waitcnt vmcnt(11)
	v_add_u32_e32 v1, v1, v5
	s_waitcnt vmcnt(10)
	v_add_u32_e32 v1, v1, v6
	s_waitcnt vmcnt(9)
	v_add_u32_e32 v1, v1, v7
	s_waitcnt vmcnt(8)
	v_add_u32_e32 v1, v1, v8
	s_waitcnt vmcnt(7)
	v_add_u32_e32 v1, v1, v9
	s_waitcnt vmcnt(6)
	v_add_u32_e32 v1, v1, v10
	s_waitcnt vmcnt(5)
	v_add_u32_e32 v1, v1, v11
	s_waitcnt vmcnt(4)
	v_add_u32_e32 v1, v1, v12
	s_waitcnt vmcnt(3)
	v_add_u32_e32 v1, v1, v13
	s_waitcnt vmcnt(2)
	v_add_u32_e32 v1, v1, v14
	s_waitcnt vmcnt(1)
	v_add_u32_e32 v1, v1, v15
	s_waitcnt vmcnt(0)
	v_add_u32_e32 v1, v1, v16
	v_cmp_eq_u32_e32 vcc, s3, v1
	s_cbranch_vccnz .LBB0_151
	s_and_b32 s7, s6, 0xff
	s_cmp_eq_u32 s7, 0
	s_mov_b64 s[66:67], -1
	s_sleep 8
	s_cbranch_scc0 .LBB0_156
	global_load_dword v1, v18, s[8:9] sc1
	s_waitcnt vmcnt(0)
	v_cmp_eq_u32_e32 vcc, 0, v1
	s_cbranch_vccnz .LBB0_158
	s_mov_b64 s[66:67], 0

.LBB0_170:
	s_and_b32 s6, s3, 0xff
	s_mov_b64 s[22:23], -1
	s_cmp_lg_u32 s6, 0
	s_mov_b64 s[26:27], -1
	s_sleep 8
	s_cbranch_scc1 .LBB0_173
	global_load_dword v1, v2, s[14:15] sc1
	s_waitcnt vmcnt(0)
	v_cmp_eq_u32_e32 vcc, 0, v1
	s_cbranch_vccnz .LBB0_175
	s_mov_b64 s[26:27], 0
	s_mov_b64 s[24:25], -1

.LBB0_187:
	s_and_b32 s6, s3, 0xff
	s_cmp_lg_u32 s6, 0
	s_mov_b64 s[24:25], -1
	s_sleep 8
	s_cbranch_scc1 .LBB0_190
	global_load_dword v1, v2, s[14:15] sc1
	s_waitcnt vmcnt(0)
	v_cmp_eq_u32_e32 vcc, 0, v1
	s_cbranch_vccnz .LBB0_192
	s_mov_b64 s[24:25], 0
	s_mov_b64 s[22:23], -1

.LBB0_273:
	global_load_dword v17, v18, s[10:11] sc1
	global_load_dword v2, v18, s[12:13] sc1
	global_load_dword v3, v18, s[14:15] sc1
	global_load_dword v4, v18, s[16:17] sc1
	global_load_dword v5, v18, s[18:19] sc1
	global_load_dword v6, v18, s[20:21] sc1
	global_load_dword v7, v18, s[22:23] sc1
	global_load_dword v8, v18, s[24:25] sc1
	global_load_dword v9, v18, s[26:27] sc1
	global_load_dword v10, v18, s[28:29] sc1
	global_load_dword v11, v18, s[30:31] sc1
	global_load_dword v12, v18, s[34:35] sc1
	global_load_dword v13, v18, s[36:37] sc1
	global_load_dword v14, v18, s[38:39] sc1
	global_load_dword v15, v18, s[40:41] sc1
	global_load_dword v16, v18, s[42:43] sc1
	s_mov_b64 s[44:45], -1
	s_mov_b64 s[46:47], -1
	s_waitcnt vmcnt(14)
	v_add_u32_e32 v1, v2, v17
	s_waitcnt vmcnt(13)
	v_add_u32_e32 v1, v1, v3
	s_waitcnt vmcnt(12)
	v_add_u32_e32 v1, v1, v4
	s_waitcnt vmcnt(11)
	v_add_u32_e32 v1, v1, v5
	s_waitcnt vmcnt(10)
	v_add_u32_e32 v1, v1, v6
	s_waitcnt vmcnt(9)
	v_add_u32_e32 v1, v1, v7
	s_waitcnt vmcnt(8)
	v_add_u32_e32 v1, v1, v8
	s_waitcnt vmcnt(7)
	v_add_u32_e32 v1, v1, v9
	s_waitcnt vmcnt(6)
	v_add_u32_e32 v1, v1, v10
	s_waitcnt vmcnt(5)
	v_add_u32_e32 v1, v1, v11
	s_waitcnt vmcnt(4)
	v_add_u32_e32 v1, v1, v12
	s_waitcnt vmcnt(3)
	v_add_u32_e32 v1, v1, v13
	s_waitcnt vmcnt(2)
	v_add_u32_e32 v1, v1, v14
	s_waitcnt vmcnt(1)
	v_add_u32_e32 v1, v1, v15
	s_waitcnt vmcnt(0)
	v_add_u32_e32 v1, v1, v16
	v_cmp_eq_u32_e32 vcc, s3, v1
	s_cbranch_vccnz .LBB0_272
	s_and_b32 s7, s6, 0xff
	s_cmp_eq_u32 s7, 0
	s_mov_b64 s[52:53], -1
	s_sleep 8
	s_cbranch_scc0 .LBB0_277
	global_load_dword v1, v18, s[8:9] sc1
	s_waitcnt vmcnt(0)
	v_cmp_eq_u32_e32 vcc, 0, v1
	s_cbranch_vccnz .LBB0_279
	s_mov_b64 s[52:53], 0

.LBB0_380:
	global_load_dword v17, v18, s[10:11] sc1
	global_load_dword v2, v18, s[12:13] sc1
	global_load_dword v3, v18, s[14:15] sc1
	global_load_dword v4, v18, s[16:17] sc1
	global_load_dword v5, v18, s[18:19] sc1
	global_load_dword v6, v18, s[20:21] sc1
	global_load_dword v7, v18, s[22:23] sc1
	global_load_dword v8, v18, s[24:25] sc1
	global_load_dword v9, v18, s[26:27] sc1
	global_load_dword v10, v18, s[28:29] sc1
	global_load_dword v11, v18, s[30:31] sc1
	global_load_dword v12, v18, s[34:35] sc1
	global_load_dword v13, v18, s[36:37] sc1
	global_load_dword v14, v18, s[38:39] sc1
	global_load_dword v15, v18, s[40:41] sc1
	global_load_dword v16, v18, s[42:43] sc1
	s_mov_b64 s[44:45], -1
	s_mov_b64 s[46:47], -1
	s_waitcnt vmcnt(14)
	v_add_u32_e32 v1, v2, v17
	s_waitcnt vmcnt(13)
	v_add_u32_e32 v1, v1, v3
	s_waitcnt vmcnt(12)
	v_add_u32_e32 v1, v1, v4
	s_waitcnt vmcnt(11)
	v_add_u32_e32 v1, v1, v5
	s_waitcnt vmcnt(10)
	v_add_u32_e32 v1, v1, v6
	s_waitcnt vmcnt(9)
	v_add_u32_e32 v1, v1, v7
	s_waitcnt vmcnt(8)
	v_add_u32_e32 v1, v1, v8
	s_waitcnt vmcnt(7)
	v_add_u32_e32 v1, v1, v9
	s_waitcnt vmcnt(6)
	v_add_u32_e32 v1, v1, v10
	s_waitcnt vmcnt(5)
	v_add_u32_e32 v1, v1, v11
	s_waitcnt vmcnt(4)
	v_add_u32_e32 v1, v1, v12
	s_waitcnt vmcnt(3)
	v_add_u32_e32 v1, v1, v13
	s_waitcnt vmcnt(2)
	v_add_u32_e32 v1, v1, v14
	s_waitcnt vmcnt(1)
	v_add_u32_e32 v1, v1, v15
	s_waitcnt vmcnt(0)
	v_add_u32_e32 v1, v1, v16
	v_cmp_eq_u32_e32 vcc, s3, v1
	s_cbranch_vccnz .LBB0_379
	s_and_b32 s7, s6, 0xff
	s_cmp_eq_u32 s7, 0
	s_mov_b64 s[48:49], -1
	s_sleep 8
	s_cbranch_scc0 .LBB0_384
	global_load_dword v1, v18, s[8:9] sc1
	s_waitcnt vmcnt(0)
	v_cmp_eq_u32_e32 vcc, 0, v1
	s_cbranch_vccnz .LBB0_386
	s_mov_b64 s[48:49], 0

.LBB0_483:
	s_sleep 8
	global_load_dword v1, v2, s[8:9] offset:32 sc1
	s_waitcnt vmcnt(0)
	v_and_b32_e32 v1, 0xffff0000, v1
	v_cmp_ne_u32_e32 vcc, v1, v3
	s_or_b64 s[12:13], vcc, s[12:13]
	s_andn2_b64 exec, exec, s[12:13]
	s_cbranch_execnz .LBB0_483

.LBB0_491:
	global_load_dword v17, v18, s[12:13] sc1
	global_load_dword v2, v18, s[14:15] sc1
	global_load_dword v3, v18, s[16:17] sc1
	global_load_dword v4, v18, s[18:19] sc1
	global_load_dword v5, v18, s[20:21] sc1
	global_load_dword v6, v18, s[22:23] sc1
	global_load_dword v7, v18, s[24:25] sc1
	global_load_dword v8, v18, s[26:27] sc1
	global_load_dword v9, v18, s[28:29] sc1
	global_load_dword v10, v18, s[30:31] sc1
	global_load_dword v11, v18, s[34:35] sc1
	global_load_dword v12, v18, s[36:37] sc1
	global_load_dword v13, v18, s[38:39] sc1
	global_load_dword v14, v18, s[40:41] sc1
	global_load_dword v15, v18, s[42:43] sc1
	global_load_dword v16, v18, s[44:45] sc1
	s_mov_b64 s[46:47], -1
	s_mov_b64 s[48:49], -1
	s_waitcnt vmcnt(14)
	v_add_u32_e32 v1, v2, v17
	s_waitcnt vmcnt(13)
	v_add_u32_e32 v1, v1, v3
	s_waitcnt vmcnt(12)
	v_add_u32_e32 v1, v1, v4
	s_waitcnt vmcnt(11)
	v_add_u32_e32 v1, v1, v5
	s_waitcnt vmcnt(10)
	v_add_u32_e32 v1, v1, v6
	s_waitcnt vmcnt(9)
	v_add_u32_e32 v1, v1, v7
	s_waitcnt vmcnt(8)
	v_add_u32_e32 v1, v1, v8
	s_waitcnt vmcnt(7)
	v_add_u32_e32 v1, v1, v9
	s_waitcnt vmcnt(6)
	v_add_u32_e32 v1, v1, v10
	s_waitcnt vmcnt(5)
	v_add_u32_e32 v1, v1, v11
	s_waitcnt vmcnt(4)
	v_add_u32_e32 v1, v1, v12
	s_waitcnt vmcnt(3)
	v_add_u32_e32 v1, v1, v13
	s_waitcnt vmcnt(2)
	v_add_u32_e32 v1, v1, v14
	s_waitcnt vmcnt(1)
	v_add_u32_e32 v1, v1, v15
	s_waitcnt vmcnt(0)
	v_add_u32_e32 v1, v1, v16
	v_cmp_eq_u32_e32 vcc, s3, v1
	s_cbranch_vccnz .LBB0_490
	s_and_b32 s7, s6, 0xff
	s_cmp_eq_u32 s7, 0
	s_mov_b64 s[50:51], -1
	s_sleep 8
	s_cbranch_scc0 .LBB0_495
	global_load_dword v1, v18, s[8:9] sc1
	s_waitcnt vmcnt(0)
	v_cmp_eq_u32_e32 vcc, 0, v1
	s_cbranch_vccnz .LBB0_497
	s_mov_b64 s[50:51], 0

.LBB0_1363:
	s_sleep 8
	global_load_dword v2, v0, s[8:9] offset:32 sc1
	s_waitcnt vmcnt(0)
	v_and_b32_e32 v2, 0xffff0000, v2
	v_cmp_ne_u32_e32 vcc, v2, v1
	s_or_b64 s[12:13], vcc, s[12:13]
	s_andn2_b64 exec, exec, s[12:13]
	s_cbranch_execnz .LBB0_1363

.LBB0_1371:
	global_load_dword v15, v16, s[8:9] sc1
	global_load_dword v0, v16, s[12:13] sc1
	global_load_dword v1, v16, s[14:15] sc1
	global_load_dword v2, v16, s[16:17] sc1
	global_load_dword v3, v16, s[18:19] sc1
	global_load_dword v4, v16, s[20:21] sc1
	global_load_dword v5, v16, s[22:23] sc1
	global_load_dword v6, v16, s[24:25] sc1
	global_load_dword v7, v16, s[26:27] sc1
	global_load_dword v8, v16, s[28:29] sc1
	global_load_dword v9, v16, s[30:31] sc1
	global_load_dword v10, v16, s[34:35] sc1
	global_load_dword v11, v16, s[36:37] sc1
	global_load_dword v12, v16, s[38:39] sc1
	global_load_dword v13, v16, s[40:41] sc1
	global_load_dword v14, v16, s[42:43] sc1
	s_mov_b64 s[44:45], -1
	s_mov_b64 s[46:47], -1
	s_waitcnt vmcnt(14)
	v_add_u32_e32 v17, v0, v15
	s_waitcnt vmcnt(13)
	v_add_u32_e32 v17, v17, v1
	s_waitcnt vmcnt(12)
	v_add_u32_e32 v17, v17, v2
	s_waitcnt vmcnt(11)
	v_add_u32_e32 v17, v17, v3
	s_waitcnt vmcnt(10)
	v_add_u32_e32 v17, v17, v4
	s_waitcnt vmcnt(9)
	v_add_u32_e32 v17, v17, v5
	s_waitcnt vmcnt(8)
	v_add_u32_e32 v17, v17, v6
	s_waitcnt vmcnt(7)
	v_add_u32_e32 v17, v17, v7
	s_waitcnt vmcnt(6)
	v_add_u32_e32 v17, v17, v8
	s_waitcnt vmcnt(5)
	v_add_u32_e32 v17, v17, v9
	s_waitcnt vmcnt(4)
	v_add_u32_e32 v17, v17, v10
	s_waitcnt vmcnt(3)
	v_add_u32_e32 v17, v17, v11
	s_waitcnt vmcnt(2)
	v_add_u32_e32 v17, v17, v12
	s_waitcnt vmcnt(1)
	v_add_u32_e32 v17, v17, v13
	s_waitcnt vmcnt(0)
	v_add_u32_e32 v17, v17, v14
	v_cmp_eq_u32_e32 vcc, s3, v17
	s_cbranch_vccnz .LBB0_1370
	s_and_b32 s44, s50, 0xff
	s_cmp_eq_u32 s44, 0
	s_mov_b64 s[44:45], -1
	s_mov_b64 s[48:49], -1
	s_sleep 8
	s_cbranch_scc0 .LBB0_1375
	global_load_dword v17, v16, s[6:7] sc1
	s_waitcnt vmcnt(0)
	v_cmp_eq_u32_e32 vcc, 0, v17
	s_cbranch_vccnz .LBB0_1377
	s_mov_b64 s[48:49], 0

.LBB0_1389:
	s_and_b32 s24, s3, 0xff
	s_mov_b64 s[22:23], -1
	s_cmp_lg_u32 s24, 0
	s_mov_b64 s[26:27], -1
	s_sleep 8
	s_cbranch_scc1 .LBB0_1392
	global_load_dword v2, v0, s[14:15] sc1
	s_waitcnt vmcnt(0)
	v_cmp_eq_u32_e32 vcc, 0, v2
	s_cbranch_vccnz .LBB0_1394
	s_mov_b64 s[26:27], 0
	s_mov_b64 s[24:25], -1

.LBB0_1406:
	s_and_b32 s22, s3, 0xff
	s_cmp_lg_u32 s22, 0
	s_mov_b64 s[24:25], -1
	s_sleep 8
	s_cbranch_scc1 .LBB0_1409
	global_load_dword v1, v0, s[14:15] sc1
	s_waitcnt vmcnt(0)
	v_cmp_eq_u32_e32 vcc, 0, v1
	s_cbranch_vccnz .LBB0_1411
	s_mov_b64 s[24:25], 0
	s_mov_b64 s[22:23], -1
